# candD + stream-task prologue: the 8 per-query q loads issued together (counted waits) instead of 8 serialized load+wait pairs
# baseline (speedup 1.0000x reference)
; __device__ __forceinline__ float bf_lo(unsigned w) { return __uint_as_float(w << 16); }
; __device__ __forceinline__ float bf_hi(unsigned w) { return __uint_as_float(w & 0xffff0000u); }
; __device__ __forceinline__ float alibi_slope(int h) { return exp2f(-(float)(h + 1)); }
; __device__ __forceinline__ float row_sum_f(float v) { v += dpp_f<0x128>(v); v += dpp_f<0x124>(v); v += dpp_f<0x122>(v); v += dpp_f<0x121>(v); return v; }
; __device__ __forceinline__ void stream_task(const Args& a, const int task, const int wave, const float kbA, LAS unsigned* rb, unsigned& ep) {
;     ...
;             const int b = task >> 1, hh = task & 1, hd = 4 * hh + (lane >> 4), dl = 4 * (lane & 15);
;             const float slope2 = alibi_slope(hd) * LOG2E;
;             f32x4 q[8], O[8]; float M[8], l[8];
; #pragma unroll
;             for (int i = 0; i < 8; ++i) {
;                 const u32x2 qr = *(const u32x2*)(QA + (size_t)(NTP + b * DS + i) * 512 + hd * 64 + dl);
;                 q[i] = (f32x4){bf_lo(qr.x), bf_hi(qr.x), bf_lo(qr.y), bf_hi(qr.y)};
;                 M[i] = sqrtf(row_sum_f(q[i][0] * q[i][0] + q[i][1] * q[i][1] + q[i][2] * q[i][2] + q[i][3] * q[i][3])) * kbA;
;                 O[i] = (f32x4){0.f, 0.f, 0.f, 0.f}; l[i] = 0.f;
;             }
.LBB0_1131:
	s_ashr_i32 s18, s30, 1
	s_lshl_b32 s0, s30, 2
	v_and_or_b32 v6, s0, 4, v89
	s_lshl_b32 s0, s18, 3
	s_add_i32 s86, s0, 0x4000
	v_lshlrev_b32_e32 v66, 7, v6
	s_ashr_i32 s87, s86, 31
	v_lshl_add_u64 v[2:3], v[116:117], 0, v[66:67]
	s_lshl_b64 s[16:17], s[86:87], 10
	v_lshl_add_u64 v[4:5], v[2:3], 0, s[16:17]
	global_load_dwordx2 v[200:201], v[4:5], off
	s_ashr_i32 s1, s0, 31
	s_lshl_b64 s[0:1], s[0:1], 10
	v_lshl_add_u64 v[2:3], v[2:3], 0, s[0:1]
	s_mov_b32 s0, 0x1000000
	v_add_co_u32_e32 v220, vcc, s0, v2
	s_mov_b32 s0, 0x1001000
	s_nop 0
	v_addc_co_u32_e32 v221, vcc, 0, v3, vcc
	v_add_co_u32_e32 v222, vcc, s0, v2
	s_nop 1
	v_addc_co_u32_e32 v223, vcc, 0, v3, vcc
	global_load_dwordx2 v[202:203], v[220:221], off offset:1024
	global_load_dwordx2 v[204:205], v[220:221], off offset:2048
	global_load_dwordx2 v[206:207], v[220:221], off offset:3072
	global_load_dwordx2 v[208:209], v[222:223], off
	global_load_dwordx2 v[210:211], v[222:223], off offset:1024
	global_load_dwordx2 v[212:213], v[222:223], off offset:2048
	global_load_dwordx2 v[214:215], v[222:223], off offset:3072
	s_mov_b32 s0, 0x1000000
	v_mov_b32_e32 v22, 0
	s_waitcnt vmcnt(7)
	v_mov_b64_e32 v[4:5], v[200:201]
	v_lshlrev_b32_e32 v38, 16, v4
	v_and_b32_e32 v39, 0xffff0000, v4
	v_and_b32_e32 v41, 0xffff0000, v5
	v_lshlrev_b32_e32 v40, 16, v5
	v_pk_mul_f32 v[4:5], v[38:39], v[38:39]
	v_pk_mul_f32 v[8:9], v[40:41], v[40:41]
	v_add_f32_e32 v4, v4, v5
	v_add_f32_e32 v4, v8, v4
	v_add_f32_e32 v4, v9, v4
	v_mov_b32_e32 v8, 0
	s_nop 0
	v_add_f32_dpp v4, v4, v4 row_ror:8 row_mask:0xf bank_mask:0xf bound_ctrl:1
	s_nop 1
	v_add_f32_dpp v4, v4, v4 row_ror:4 row_mask:0xf bank_mask:0xf bound_ctrl:1
	s_nop 1
	v_add_f32_dpp v7, v4, v4 row_ror:2 row_mask:0xf bank_mask:0xf bound_ctrl:1
	v_add_co_u32_e32 v4, vcc, s0, v2
	s_mov_b32 s0, 0x1001000
	s_nop 0
	v_addc_co_u32_e32 v5, vcc, 0, v3, vcc
	v_add_co_u32_e32 v2, vcc, s0, v2
	v_readlane_b32 s0, v240, 12
	s_nop 0
	v_addc_co_u32_e32 v3, vcc, 0, v3, vcc
	v_readlane_b32 s1, v240, 13
	v_mov_b32_dpp v8, v7 row_ror:1 row_mask:0xf bank_mask:0xf
	s_and_b64 vcc, exec, s[0:1]
	s_waitcnt vmcnt(6)
	v_mov_b64_e32 v[10:11], v[202:203]
	v_lshlrev_b32_e32 v34, 16, v10
	v_and_b32_e32 v35, 0xffff0000, v10
	v_and_b32_e32 v37, 0xffff0000, v11
	v_lshlrev_b32_e32 v36, 16, v11
	v_pk_mul_f32 v[10:11], v[34:35], v[34:35]
	v_pk_mul_f32 v[12:13], v[36:37], v[36:37]
	v_add_f32_e32 v9, v10, v11
	v_add_f32_e32 v9, v12, v9
	v_add_f32_e32 v9, v13, v9
	v_mov_b32_e32 v10, 0
	v_add_f32_dpp v9, v9, v9 row_ror:8 row_mask:0xf bank_mask:0xf bound_ctrl:1
	s_waitcnt vmcnt(5)
	v_mov_b64_e32 v[12:13], v[204:205]
	v_lshlrev_b32_e32 v142, 16, v12
	v_and_b32_e32 v143, 0xffff0000, v12
	v_and_b32_e32 v141, 0xffff0000, v13
	v_lshlrev_b32_e32 v140, 16, v13
	v_pk_mul_f32 v[12:13], v[142:143], v[142:143]
	v_pk_mul_f32 v[14:15], v[140:141], v[140:141]
	v_add_f32_e32 v11, v12, v13
	s_waitcnt vmcnt(4)
	v_mov_b64_e32 v[4:5], v[206:207]
	v_lshlrev_b32_e32 v136, 16, v4
	v_and_b32_e32 v137, 0xffff0000, v4
	v_add_f32_e32 v11, v14, v11
	v_and_b32_e32 v139, 0xffff0000, v5
	v_lshlrev_b32_e32 v138, 16, v5
	v_pk_mul_f32 v[4:5], v[136:137], v[136:137]
	v_add_f32_e32 v11, v15, v11
	v_pk_mul_f32 v[14:15], v[138:139], v[138:139]
	v_add_f32_e32 v4, v4, v5
	v_add_f32_e32 v4, v14, v4
	v_add_f32_e32 v4, v15, v4
	v_add_f32_dpp v11, v11, v11 row_ror:8 row_mask:0xf bank_mask:0xf bound_ctrl:1
	v_add_f32_dpp v9, v9, v9 row_ror:4 row_mask:0xf bank_mask:0xf bound_ctrl:1
	v_add_f32_dpp v4, v4, v4 row_ror:8 row_mask:0xf bank_mask:0xf bound_ctrl:1
	v_add_f32_dpp v11, v11, v11 row_ror:4 row_mask:0xf bank_mask:0xf bound_ctrl:1
	v_add_f32_dpp v9, v9, v9 row_ror:2 row_mask:0xf bank_mask:0xf bound_ctrl:1
	v_add_f32_dpp v4, v4, v4 row_ror:4 row_mask:0xf bank_mask:0xf bound_ctrl:1
	v_add_f32_dpp v11, v11, v11 row_ror:2 row_mask:0xf bank_mask:0xf bound_ctrl:1
	v_mov_b32_e32 v12, 0
	v_add_f32_dpp v13, v4, v4 row_ror:2 row_mask:0xf bank_mask:0xf bound_ctrl:1
	v_mov_b32_e32 v14, 0
	v_mov_b32_dpp v10, v9 row_ror:1 row_mask:0xf bank_mask:0xf
	v_mov_b32_dpp v12, v11 row_ror:1 row_mask:0xf bank_mask:0xf
	v_mov_b32_dpp v14, v13 row_ror:1 row_mask:0xf bank_mask:0xf
	s_waitcnt vmcnt(3)
	v_mov_b64_e32 v[4:5], v[208:209]
	v_lshlrev_b32_e32 v128, 16, v4
	v_and_b32_e32 v129, 0xffff0000, v4
	v_and_b32_e32 v131, 0xffff0000, v5
	v_lshlrev_b32_e32 v130, 16, v5
	v_pk_mul_f32 v[4:5], v[128:129], v[128:129]
	v_pk_mul_f32 v[16:17], v[130:131], v[130:131]
	v_add_f32_e32 v4, v4, v5
	v_add_f32_e32 v4, v16, v4
	v_add_f32_e32 v4, v17, v4
	v_mov_b32_e32 v16, 0
	s_nop 0
	v_add_f32_dpp v4, v4, v4 row_ror:8 row_mask:0xf bank_mask:0xf bound_ctrl:1
	s_nop 1
	v_add_f32_dpp v4, v4, v4 row_ror:4 row_mask:0xf bank_mask:0xf bound_ctrl:1
	s_nop 1
	v_add_f32_dpp v15, v4, v4 row_ror:2 row_mask:0xf bank_mask:0xf bound_ctrl:1
	s_waitcnt vmcnt(2)
	v_mov_b64_e32 v[4:5], v[210:211]
	v_lshlrev_b32_e32 v126, 16, v4
	v_and_b32_e32 v127, 0xffff0000, v4
	v_and_b32_e32 v125, 0xffff0000, v5
	v_lshlrev_b32_e32 v124, 16, v5
	v_pk_mul_f32 v[4:5], v[126:127], v[126:127]
	v_pk_mul_f32 v[18:19], v[124:125], v[124:125]
	v_add_f32_e32 v4, v4, v5
	v_add_f32_e32 v4, v18, v4
	v_add_f32_e32 v4, v19, v4
	v_mov_b32_e32 v18, 0
	v_mov_b32_dpp v16, v15 row_ror:1 row_mask:0xf bank_mask:0xf
	v_add_f32_dpp v4, v4, v4 row_ror:8 row_mask:0xf bank_mask:0xf bound_ctrl:1
	s_nop 1
	v_add_f32_dpp v4, v4, v4 row_ror:4 row_mask:0xf bank_mask:0xf bound_ctrl:1
	s_nop 1
	v_add_f32_dpp v17, v4, v4 row_ror:2 row_mask:0xf bank_mask:0xf bound_ctrl:1
	s_waitcnt vmcnt(1)
	v_mov_b64_e32 v[4:5], v[212:213]
	v_lshlrev_b32_e32 v122, 16, v4
	v_and_b32_e32 v123, 0xffff0000, v4
	v_and_b32_e32 v121, 0xffff0000, v5
	v_lshlrev_b32_e32 v120, 16, v5
	v_pk_mul_f32 v[4:5], v[122:123], v[122:123]
	v_pk_mul_f32 v[20:21], v[120:121], v[120:121]
	v_add_f32_e32 v4, v4, v5
	v_add_f32_e32 v4, v20, v4
	v_add_f32_e32 v4, v21, v4
	v_mov_b32_e32 v20, 0
	v_mov_b32_dpp v18, v17 row_ror:1 row_mask:0xf bank_mask:0xf
	v_add_f32_dpp v4, v4, v4 row_ror:8 row_mask:0xf bank_mask:0xf bound_ctrl:1
	s_waitcnt vmcnt(0)
	v_mov_b64_e32 v[2:3], v[214:215]
	v_lshlrev_b32_e32 v132, 16, v2
	v_and_b32_e32 v133, 0xffff0000, v2
	v_add_f32_dpp v4, v4, v4 row_ror:4 row_mask:0xf bank_mask:0xf bound_ctrl:1
	v_and_b32_e32 v135, 0xffff0000, v3
	v_lshlrev_b32_e32 v134, 16, v3
	v_pk_mul_f32 v[2:3], v[132:133], v[132:133]
	v_add_f32_dpp v19, v4, v4 row_ror:2 row_mask:0xf bank_mask:0xf bound_ctrl:1
	v_pk_mul_f32 v[4:5], v[134:135], v[134:135]
	v_add_f32_e32 v2, v2, v3
	v_add_f32_e32 v2, v4, v2
	v_add_f32_e32 v2, v5, v2
	v_mov_b32_dpp v20, v19 row_ror:1 row_mask:0xf bank_mask:0xf
	s_nop 0
	v_add_f32_dpp v2, v2, v2 row_ror:8 row_mask:0xf bank_mask:0xf bound_ctrl:1
	s_nop 1
	v_add_f32_dpp v2, v2, v2 row_ror:4 row_mask:0xf bank_mask:0xf bound_ctrl:1
	s_nop 1
	v_add_f32_dpp v21, v2, v2 row_ror:2 row_mask:0xf bank_mask:0xf bound_ctrl:1
	s_nop 1
	v_mov_b32_dpp v22, v21 row_ror:1 row_mask:0xf bank_mask:0xf
	s_cbranch_vccz .LBB0_1134
; __device__ __forceinline__ void stream_task(const Args& a, const int task, const int wave, const float kbA, LAS unsigned* rb, unsigned& ep) {
;     ...
;             const f32x4 qa = wave == 0 ? q[0] : wave == 1 ? q[1] : wave == 2 ? q[2] : q[3], qb = wave == 0 ? q[4] : wave == 1 ? q[5] : wave == 2 ? q[6] : q[7];
;             const float Ma = wave == 0 ? M[0] : wave == 1 ? M[1] : wave == 2 ? M[2] : M[3], Mb = wave == 0 ? M[4] : wave == 1 ? M[5] : wave == 2 ? M[6] : M[7];
	v_readlane_b32 s0, v240, 30
	v_readlane_b32 s1, v240, 31
	s_andn2_b64 vcc, exec, s[0:1]
	s_cbranch_vccnz .LBB0_1135
	v_cndmask_b32_e64 v5, v139, v141, s[8:9]
	v_cndmask_b32_e64 v4, v138, v140, s[8:9]
	v_cndmask_b32_e64 v3, v137, v143, s[8:9]
	v_cndmask_b32_e64 v2, v136, v142, s[8:9]
	s_branch .LBB0_1136
